# v115 plus LRU pass-3 next-unit inputs touched into L2 (index broadcast via LDS)
# baseline (speedup 1.0000x reference)
; template <int PASS>
; __device__ __forceinline__ void lru_unit(const LruPtrs& args, LAS unsigned char* lds, int chunk, int bl, int g, int ck) {
;     ...
;     if (PASS == 3) { typedef float f32x2v __attribute__((ext_vector_type(2))); f32x2v ag[4];
; #pragma unroll
;         for (int j = 0; j < 4; ++j) { const int cc = 4 * w + j; ag[j] = (f32x2v){1.f, 0.f}; if (cc < ck) ag[j] = *(const GAS f32x2v*)(AGG + ((size_t)(bl * 32 + cc) * D + g * 64 + lane) * 2); }
; #pragma unroll
;         for (int j = 0; j < 4; ++j) { pH = ag[j].x * pH + ag[j].y; pA = pA * ag[j].x; } }
;     ...
;     if (PASS == 1) {
; #pragma unroll
;     for (int q = 0; q < 8; ++q)
;         asm volatile("s_nop 1\n\t"
;             LRU_STEP("row_shr:1 row_mask:0xf bank_mask:0xf") LRU_STEP("row_shr:2 row_mask:0xf bank_mask:0xf") LRU_STEP("row_shr:4 row_mask:0xf bank_mask:0xf")
;             LRU_STEP("row_shr:8 row_mask:0xf bank_mask:0xf") LRU_STEP("row_bcast:15 row_mask:0xa bank_mask:0xf")
;             : "+v"(uv[q][0]), "+v"(av[q][0]), "+v"(uv[q][1]), "+v"(av[q][1]), "+v"(uv[q][2]), "+v"(av[q][2]), "+v"(uv[q][3]), "+v"(av[q][3]));
; #pragma unroll
;     for (int q = 0; q < 8; ++q) { v4u st;
; #pragma unroll
;         for (int p = 0; p < 4; ++p) st[p] = pg8::cvt_pk_bf16(av[q][p], uv[q][p]);
;         stash[q * 64] = st; }
;     }
;     ...
;     if (PASS == 1 && n == 31) {
; #pragma unroll
;         for (int q = 0; q < 8; ++q)
; #pragma unroll
;             for (int p = 0; p < 4; ++p) { const int ci = 8 * q + 4 * hi + p; WAG[(w * 64 + ci) * 2] = av[q][p]; WAG[(w * 64 + ci) * 2 + 1] = uv[q][p]; }
;     }
;     if (PASS == 3) { PART[(w * 64 + lane) * 2] = pA; PART[(w * 64 + lane) * 2 + 1] = pH; }
;     __syncthreads();
;     if (PASS == 1) {
;         if (w == 0) { float A = 1.f, H = 0.f;
; #pragma unroll
;             for (int ww = 0; ww < 8; ++ww) { const float a = WAG[(ww * 64 + lane) * 2], h = WAG[(ww * 64 + lane) * 2 + 1]; H = a * H + h; A = A * a; }
;             GAS float* dst = AGG + ((size_t)(bl * 32 + ck) * D + g * 64 + lane) * 2; dst[0] = A; dst[1] = H; }
;         __syncthreads();
;     } else {
;         if (w == 0) { float H = 0.f;
; #pragma unroll
;             for (int ww = 0; ww < 8; ++ww) H = PART[(ww * 64 + lane) * 2] * H + PART[(ww * 64 + lane) * 2 + 1];
; #pragma unroll
;             for (int ww = 0; ww < 8; ++ww) { CARW[ww * 64 + lane] = H; H = pg8::bf_lo(gagg[ww]) * H + pg8::bf_hi(gagg[ww]); } }
.LBB0_554:
	s_waitcnt vmcnt(0)
	s_and_saveexec_b64 s[100:101], s[10:11]
	v_mov_b32_e32 v180, s86
	ds_write_b32 v180, v252 offset:64
	s_or_b64 exec, exec, s[100:101]
	v_mov_b32_e32 v60, v66
	v_mov_b32_e32 v61, v90
	v_mov_b32_e32 v65, v91
	v_fmac_f32_e32 v59, 0, v58
	v_fmac_f32_e32 v63, v62, v59
	s_andn2_b32 s15, s15, 63
	v_mul_f32_e32 v66, v58, v62
	v_fmac_f32_e32 v67, v60, v63
	v_or_b32_e32 v58, s15, v70
	v_lshl_add_u32 v62, v58, 3, 0
	v_pk_mul_f32 v[58:59], v[60:61], v[66:67]
	v_mov_b32_e32 v64, v61
	v_pk_mul_f32 v[58:59], v[64:65], v[58:59]
	v_pk_fma_f32 v[60:61], v[60:61], v[66:67], v[64:65]
	s_andn2_b64 vcc, exec, s[6:7]
	v_mov_b32_e32 v59, v61
	ds_write_b64 v62, v[58:59] offset:4096
	s_waitcnt lgkmcnt(0)
	s_barrier
	s_cbranch_vccnz .LBB0_556
	v_lshl_add_u32 v66, v70, 3, 0
	ds_read2st64_b64 v[58:61], v66 offset0:8 offset1:9
	ds_read2st64_b64 v[62:65], v66 offset0:10 offset1:11
	ds_read2st64_b64 v[78:81], v66 offset0:12 offset1:13
	ds_read2st64_b64 v[82:85], v66 offset0:14 offset1:15
	v_lshlrev_b32_e32 v67, 2, v70
	s_waitcnt lgkmcnt(3)
	v_fma_f32 v58, 0, v58, v59
	v_fmac_f32_e32 v61, v58, v60
	s_waitcnt lgkmcnt(2)
	v_fma_f32 v58, v61, v62, v63
	v_fmac_f32_e32 v65, v58, v64
	s_waitcnt lgkmcnt(1)
	v_fma_f32 v58, v65, v78, v79
	v_fmac_f32_e32 v81, v58, v80
	s_waitcnt lgkmcnt(0)
	v_fma_f32 v58, v81, v82, v83
	v_fmac_f32_e32 v85, v58, v84
	v_lshlrev_b32_e32 v59, 16, v77
	v_and_b32_e32 v60, 0xffff0000, v77
	v_sub_u32_e32 v58, v66, v67
	v_fmac_f32_e32 v60, v85, v59
	v_lshlrev_b32_e32 v59, 16, v75
	v_and_b32_e32 v61, 0xffff0000, v75
	ds_write2st64_b32 v58, v85, v60 offset0:32 offset1:33
	v_fmac_f32_e32 v61, v60, v59
	v_lshlrev_b32_e32 v59, 16, v74
	v_and_b32_e32 v60, 0xffff0000, v74
	v_fmac_f32_e32 v60, v61, v59
	ds_write2st64_b32 v58, v61, v60 offset0:34 offset1:35
	v_lshlrev_b32_e32 v59, 16, v73
	v_and_b32_e32 v61, 0xffff0000, v73
	v_fmac_f32_e32 v61, v60, v59
	v_lshlrev_b32_e32 v59, 16, v72
	v_and_b32_e32 v60, 0xffff0000, v72
	v_fmac_f32_e32 v60, v61, v59
	ds_write2st64_b32 v58, v61, v60 offset0:36 offset1:37
	v_lshlrev_b32_e32 v59, 16, v71
	v_and_b32_e32 v61, 0xffff0000, v71
	v_fmac_f32_e32 v61, v60, v59
	v_lshlrev_b32_e32 v59, 16, v76
	v_and_b32_e32 v60, 0xffff0000, v76
	v_fmac_f32_e32 v60, v61, v59
	ds_write2st64_b32 v58, v61, v60 offset0:38 offset1:39
.LBB0_556:
	v_mov_b32_e32 v180, s86
	ds_read_b32 v180, v180 offset:64
	s_waitcnt lgkmcnt(0)
	v_readfirstlane_b32 s98, v180
	s_add_i32 s98, s98, 0xfffffc00
	s_cmp_ge_u32 s98, 0x400
	s_cbranch_scc1 .Ll3pf_skip
	s_lshr_b32 s100, s98, 9
	s_lshl_b32 s100, s100, 13
	s_and_b32 s101, s98, 31
	s_lshl_b32 s101, s101, 8
	s_or_b32 s100, s100, s101
	v_bfe_u32 v181, v236, 3, 3
	v_and_b32_e32 v182, 0x1c0, v236
	v_lshrrev_b32_e32 v183, 1, v182
	v_add3_u32 v181, v181, v183, s100
	s_bfe_u32 s100, s98, 0x40005
	s_lshl_b32 s100, s100, 7
	s_add_i32 s100, s100, s88
	v_and_b32_e32 v183, 7, v236
	v_lshlrev_b32_e32 v183, 4, v183
	v_add_u32_e32 v183, s100, v183
	v_lshl_add_u32 v181, v181, 11, v183
	v_lshrrev_b32_e32 v182, 6, v182
	s_lshl_b32 s100, s98, 3
	v_add_u32_e32 v182, s100, v182
	v_lshlrev_b32_e32 v182, 13, v182
	v_and_b32_e32 v183, 63, v236
	v_lshl_add_u32 v182, v183, 4, v182
	v_add_u32_e32 v182, 0x16000000, v182
	v_add_u32_e32 v186, 0x1000, v182
	s_add_u32 s100, s12, 0x13c00000
	s_addc_u32 s101, s13, 0
	v_add_u32_e32 v183, 0x4000, v181
	v_add_u32_e32 v184, 0x8000, v181
	v_add_u32_e32 v185, 0xc000, v181
	global_load_dwordx4 v[188:191], v181, s[100:101]
	global_load_dwordx4 v[188:191], v183, s[100:101]
	global_load_dwordx4 v[188:191], v184, s[100:101]
	global_load_dwordx4 v[188:191], v185, s[100:101]
	global_load_dwordx4 v[188:191], v182, s[100:101]
	global_load_dwordx4 v[188:191], v182, s[100:101] offset:1024
	global_load_dwordx4 v[188:191], v182, s[100:101] offset:2048
	global_load_dwordx4 v[188:191], v182, s[100:101] offset:3072
	global_load_dwordx4 v[188:191], v186, s[100:101]
	global_load_dwordx4 v[188:191], v186, s[100:101] offset:1024
	global_load_dwordx4 v[188:191], v186, s[100:101] offset:2048
	global_load_dwordx4 v[188:191], v186, s[100:101] offset:3072
